# LRU pass-1 sub-chunk loop: counted wait vmcnt(4) retires the prefetched conv rows without waiting for the 4 write-through LAB stores issued after them
# speedup vs baseline: 1.0033x; 1.0033x over previous
.LBB0_337:
	s_and_b32 s43, s58, 1
	s_and_b64 s[8:9], s[8:9], exec
	s_cselect_b32 s33, s3, s11
	s_movk_i32 s3, 0x1000
	s_cselect_b32 s3, 0x100, s3
	s_ashr_i32 s11, s10, 31
	s_lshl_b64 s[8:9], s[10:11], 10
	s_ashr_i32 s10, s10, 4
	s_ashr_i32 s11, s10, 31
	s_lshl_b64 s[10:11], s[10:11], 15
	s_add_u32 s12, s4, s8
	v_and_b32_e32 v184, 15, v2
	v_ashrrev_i32_e32 v3, 4, v2
	s_addc_u32 s13, s5, s9
	s_lshl_b32 s8, s43, 17
	s_add_u32 s8, s78, s8
	s_waitcnt vmcnt(5)
	v_lshlrev_b32_e32 v16, 6, v184
	v_lshlrev_b32_e32 v4, 3, v3
	s_addc_u32 s9, s42, 0
	v_add_u32_e32 v6, v16, v4
	s_add_u32 s14, s8, 0x10000
	v_ashrrev_i32_e32 v7, 31, v6
	s_addc_u32 s15, s9, 0
	v_lshlrev_b64 v[8:9], 1, v[6:7]
	v_add_u32_e32 v12, 32, v6
	v_lshl_add_u64 v[10:11], s[8:9], 0, v[8:9]
	v_lshl_add_u64 v[8:9], s[14:15], 0, v[8:9]
	v_ashrrev_i32_e32 v13, 31, v12
	global_load_dwordx4 v[34:37], v[10:11], off
	global_load_dwordx4 v[38:41], v[10:11], off offset:64
	v_lshl_add_u64 v[12:13], v[12:13], 1, s[14:15]
	global_load_dwordx4 v[42:45], v[8:9], off
	global_load_dwordx4 v[46:49], v[12:13], off
	v_add_u32_e32 v8, 0x400, v6
	v_ashrrev_i32_e32 v9, 31, v8
	v_add_u32_e32 v12, 0x420, v6
	v_lshl_add_u64 v[8:9], v[8:9], 1, s[14:15]
	v_ashrrev_i32_e32 v13, 31, v12
	global_load_dwordx4 v[50:53], v[10:11], off offset:2048
	global_load_dwordx4 v[54:57], v[10:11], off offset:2112
	v_lshl_add_u64 v[10:11], v[12:13], 1, s[14:15]
	global_load_dwordx4 v[58:61], v[8:9], off
	global_load_dwordx4 v[62:65], v[10:11], off
	v_add_u32_e32 v8, 0x800, v6
	v_ashrrev_i32_e32 v9, 31, v8
	v_lshlrev_b64 v[8:9], 1, v[8:9]
	v_lshl_add_u64 v[10:11], s[8:9], 0, v[8:9]
	v_lshl_add_u64 v[8:9], s[14:15], 0, v[8:9]
	global_load_dwordx4 v[66:69], v[10:11], off
	global_load_dwordx4 v[70:73], v[8:9], off
	v_add_u32_e32 v8, 0x820, v6
	v_ashrrev_i32_e32 v9, 31, v8
	v_lshlrev_b64 v[8:9], 1, v[8:9]
	v_lshl_add_u64 v[10:11], s[8:9], 0, v[8:9]
	v_lshl_add_u64 v[8:9], s[14:15], 0, v[8:9]
	global_load_dwordx4 v[74:77], v[10:11], off
	global_load_dwordx4 v[78:81], v[8:9], off
	v_add_u32_e32 v8, 0xc00, v6
	v_ashrrev_i32_e32 v9, 31, v8
	v_add_u32_e32 v6, 0xc20, v6
	v_lshlrev_b64 v[8:9], 1, v[8:9]
	v_ashrrev_i32_e32 v7, 31, v6
	v_or_b32_e32 v186, s33, v184
	v_lshl_add_u64 v[10:11], s[8:9], 0, v[8:9]
	v_lshl_add_u64 v[8:9], s[14:15], 0, v[8:9]
	v_lshlrev_b64 v[6:7], 1, v[6:7]
	v_add_u32_e32 v5, -2, v186
	global_load_dwordx4 v[82:85], v[10:11], off
	global_load_dwordx4 v[86:89], v[8:9], off
	v_lshl_add_u64 v[8:9], s[8:9], 0, v[6:7]
	v_cmp_lt_i32_e32 vcc, 1, v186
	v_cmp_gt_i32_e64 s[8:9], s3, v5
	v_lshl_add_u64 v[6:7], s[14:15], 0, v[6:7]
	v_add_u32_e32 v0, -2, v184
	s_and_b64 vcc, vcc, s[8:9]
	global_load_dwordx4 v[90:93], v[8:9], off
	global_load_dwordx4 v[94:97], v[6:7], off
	v_cndmask_b32_e32 v6, v184, v0, vcc
	v_cmp_lt_i32_e32 vcc, 0, v186
	v_cmp_ge_i32_e64 s[8:9], s3, v186
	v_ashrrev_i32_e32 v5, 31, v4
	s_and_b64 vcc, vcc, s[8:9]
	v_lshlrev_b64 v[8:9], 1, v[4:5]
	v_add_u32_e32 v5, 1, v186
	v_subbrev_co_u32_e32 v10, vcc, 0, v184, vcc
	v_cmp_lt_i32_e32 vcc, -2, v186
	v_cmp_gt_i32_e64 s[8:9], s3, v5
	v_ashrrev_i32_e32 v7, 31, v6
	v_lshlrev_b32_e32 v0, 10, v184
	s_and_b64 vcc, vcc, s[8:9]
	v_lshlrev_b64 v[6:7], 10, v[6:7]
	v_ashrrev_i32_e32 v11, 31, v10
	v_lshl_add_u64 v[12:13], s[12:13], 0, v[0:1]
	v_addc_co_u32_e32 v0, vcc, 0, v184, vcc
	v_lshl_add_u64 v[6:7], s[12:13], 0, v[6:7]
	v_lshlrev_b64 v[10:11], 10, v[10:11]
	v_lshlrev_b32_e32 v0, 10, v0
	v_lshl_add_u64 v[6:7], v[6:7], 0, v[8:9]
	v_lshl_add_u64 v[10:11], s[12:13], 0, v[10:11]
	v_lshl_add_u64 v[14:15], s[12:13], 0, v[0:1]
	v_lshl_add_u64 v[10:11], v[10:11], 0, v[8:9]
	v_lshl_add_u64 v[12:13], v[12:13], 0, v[8:9]
	v_lshl_add_u64 v[14:15], v[14:15], 0, v[8:9]
	global_load_dwordx4 v[126:129], v[6:7], off
	global_load_dwordx4 v[110:113], v[6:7], off offset:64
	global_load_dwordx4 v[122:125], v[10:11], off
	global_load_dwordx4 v[106:109], v[10:11], off offset:64
	global_load_dwordx4 v[118:121], v[12:13], off
	global_load_dwordx4 v[102:105], v[12:13], off offset:64
	global_load_dwordx4 v[114:117], v[14:15], off
	global_load_dwordx4 v[98:101], v[14:15], off offset:64
	v_add_lshl_u32 v4, v4, s18, 2
	v_readlane_b32 s9, v254, 51
	v_readlane_b32 s8, v254, 50
	s_mov_b32 s37, 0
	v_add_u32_e32 v187, s9, v4
	v_add_u32_e32 v188, s8, v4
	s_or_b32 s48, s3, 2
	v_add_u32_e32 v4, 0x80, v4
	s_mov_b32 s38, s36
	s_mov_b32 s39, s37
	v_mov_b64_e32 v[10:11], s[36:37]
	s_cmp_gt_i32 s33, -1
	v_add_u32_e32 v189, s9, v4
	v_add_u32_e32 v196, s8, v4
	v_mov_b32_e32 v4, s77
	s_movk_i32 s8, 0x110
	v_mov_b64_e32 v[12:13], s[38:39]
	s_cselect_b64 s[38:39], -1, 0
	v_mad_u32_u24 v4, v184, s8, v4
	s_lshl_b32 s8, s43, 9
	s_add_i32 s49, s3, -1
	s_add_i32 s8, s8, s18
	v_lshlrev_b32_e32 v138, 2, v3
	s_cmp_eq_u32 s43, 0
	v_and_b32_e32 v0, 48, v2
	v_and_b32_e32 v7, -16, v2
	v_add_lshl_u32 v2, s8, v138, 2
	s_cselect_b64 s[8:9], -1, 0
	s_cmp_eq_u32 s43, 1
	v_lshl_add_u64 v[140:141], s[12:13], 0, v[8:9]
	s_mul_i32 s12, s43, 0x2200000
	v_lshl_add_u32 v185, v3, 7, s76
	v_lshlrev_b32_e32 v6, 5, v3
	v_add_u32_e32 v3, 64, v2
	s_cselect_b64 s[44:45], -1, 0
	s_add_u32 s10, s12, s10
	v_add_u32_e32 v197, s41, v2
	v_add_u32_e32 v198, s68, v2
	v_add_u32_e32 v199, s69, v2
	v_add_u32_e32 v202, s41, v3
	v_add_u32_e32 v203, s68, v3
	v_add_u32_e32 v204, s69, v3
	v_add_u32_e32 v3, 0x80, v2
	v_add_u32_e32 v2, 0xc0, v2
	s_addc_u32 s11, 0, s11
	v_ashrrev_i32_e32 v139, 31, v138
	v_add_u32_e32 v205, s41, v3
	v_add_u32_e32 v206, s68, v3
	v_add_u32_e32 v207, s69, v3
	v_add_u32_e32 v208, s41, v2
	v_add_u32_e32 v209, s68, v2
	v_add_u32_e32 v210, s69, v2
	v_or_b32_e32 v2, s10, v16
	v_mov_b32_e32 v3, s11
	v_or_b32_e32 v5, 15, v0
	v_lshl_add_u64 v[2:3], v[138:139], 2, v[2:3]
	v_cndmask_b32_e64 v211, v0, v5, s[8:9]
	v_lshl_add_u64 v[142:143], s[24:25], 0, v[2:3]
	v_add_u32_e32 v212, v4, v6
	v_add_u32_e32 v213, v4, v7
	v_mov_b32_e32 v172, 1.0
	v_mov_b32_e32 v173, 1.0
	v_mov_b32_e32 v174, 1.0
	v_mov_b32_e32 v175, 1.0
	v_mov_b32_e32 v176, 1.0
	v_mov_b32_e32 v177, 1.0
	v_mov_b32_e32 v178, 1.0
	v_mov_b32_e32 v179, 1.0
	v_mov_b32_e32 v180, 1.0
	v_mov_b32_e32 v181, 1.0
	v_mov_b32_e32 v182, 1.0
	v_mov_b32_e32 v183, 1.0
	v_mov_b32_e32 v192, 1.0
	v_mov_b32_e32 v193, 1.0
	v_mov_b32_e32 v194, 1.0
	v_mov_b32_e32 v195, 1.0
	v_mov_b32_e32 v214, 0
	v_mov_b32_e32 v215, 0
	v_mov_b32_e32 v216, 0
	v_mov_b32_e32 v217, 0
	v_mov_b32_e32 v218, 0
	v_mov_b32_e32 v219, 0
	v_mov_b32_e32 v220, 0
	v_mov_b32_e32 v221, 0
	v_mov_b32_e32 v222, 0
	v_mov_b32_e32 v223, 0
	v_mov_b32_e32 v224, 0
	v_mov_b32_e32 v225, 0
	v_mov_b32_e32 v234, 0
	v_mov_b32_e32 v235, 0
	v_mov_b32_e32 v236, 0
	v_mov_b32_e32 v237, 0
	s_waitcnt vmcnt(0)
	s_branch .LBB0_339

.LBB0_339:
	ds_read_b128 v[2:5], v187
	ds_read_b128 v[6:9], v187 offset:16
	ds_read_b128 v[14:17], v189
	ds_read_b128 v[10:13], v189 offset:16
	ds_read_b128 v[144:147], v188
	ds_read_b128 v[148:151], v188 offset:16
	ds_read_b128 v[152:155], v196
	ds_read_b128 v[156:159], v196 offset:16
	ds_read_b128 v[160:163], v188 offset:2048
	ds_read_b128 v[164:167], v188 offset:2064
	ds_read_b128 v[130:133], v196 offset:2048
	ds_read_b128 v[134:137], v196 offset:2064
	s_mov_b32 s40, s37
	v_add_u32_e32 v0, s40, v186
	v_cmp_lt_i32_e32 vcc, 1, v0
	v_cmp_gt_i32_e64 s[10:11], s48, v0
	s_and_b64 s[14:15], vcc, s[10:11]
	v_cmp_lt_i32_e32 vcc, 0, v0
	v_cmp_ge_i32_e64 s[10:11], s3, v0
	s_and_b64 s[10:11], vcc, s[10:11]
	v_cmp_gt_i32_e32 vcc, s3, v0
	s_and_b64 s[12:13], s[38:39], vcc
	v_cmp_lt_i32_e32 vcc, -2, v0
	v_cmp_gt_i32_e64 s[16:17], s49, v0
	s_and_b64 vcc, vcc, s[16:17]
	s_and_b64 s[16:17], s[14:15], s[10:11]
	s_and_b64 s[16:17], s[16:17], s[12:13]
	s_and_b64 s[16:17], s[16:17], vcc
	s_cmp_eq_u64 s[16:17], exec
	s_waitcnt vmcnt(4)
	s_cbranch_scc1 .Lconv_nomask
	v_cndmask_b32_e64 v126, 0, v126, s[14:15]
	v_cndmask_b32_e64 v127, 0, v127, s[14:15]
	v_cndmask_b32_e64 v128, 0, v128, s[14:15]
	v_cndmask_b32_e64 v129, 0, v129, s[14:15]
	v_cndmask_b32_e64 v110, 0, v110, s[14:15]
	v_cndmask_b32_e64 v111, 0, v111, s[14:15]
	v_cndmask_b32_e64 v112, 0, v112, s[14:15]
	v_cndmask_b32_e64 v113, 0, v113, s[14:15]
	v_cndmask_b32_e64 v122, 0, v122, s[10:11]
	v_cndmask_b32_e64 v123, 0, v123, s[10:11]
	v_cndmask_b32_e64 v124, 0, v124, s[10:11]
	v_cndmask_b32_e64 v125, 0, v125, s[10:11]
	v_cndmask_b32_e64 v106, 0, v106, s[10:11]
	v_cndmask_b32_e64 v107, 0, v107, s[10:11]
	v_cndmask_b32_e64 v108, 0, v108, s[10:11]
	v_cndmask_b32_e64 v109, 0, v109, s[10:11]
	v_cndmask_b32_e64 v118, 0, v118, s[12:13]
	v_cndmask_b32_e64 v119, 0, v119, s[12:13]
	v_cndmask_b32_e64 v120, 0, v120, s[12:13]
	v_cndmask_b32_e64 v121, 0, v121, s[12:13]
	v_cndmask_b32_e64 v102, 0, v102, s[12:13]
	v_cndmask_b32_e64 v103, 0, v103, s[12:13]
	v_cndmask_b32_e64 v104, 0, v104, s[12:13]
	v_cndmask_b32_e64 v105, 0, v105, s[12:13]
	v_cndmask_b32_e32 v114, 0, v114, vcc
	v_cndmask_b32_e32 v115, 0, v115, vcc
	v_cndmask_b32_e32 v116, 0, v116, vcc
	v_cndmask_b32_e32 v117, 0, v117, vcc
	v_cndmask_b32_e32 v98, 0, v98, vcc
	v_cndmask_b32_e32 v99, 0, v99, vcc
	v_cndmask_b32_e32 v100, 0, v100, vcc
	v_cndmask_b32_e32 v101, 0, v101, vcc
